# ctx-row split-K partial sums: 32 partial loads per row issued together in both LN passes (was 16 serialized round trips on the slowest waves)
# speedup vs baseline: 1.0012x; 1.0012x over previous
.LBB0_1560:
	s_cmp_eq_u64 s[4:5], 0
	v_lshlrev_b32_e32 v34, 2, v38
	v_ashrrev_i32_e32 v35, 31, v34
	v_lshl_add_u64 v[2:3], v[34:35], 2, s[20:21]
	global_load_dwordx4 v[30:33], v[2:3], off
	global_load_dwordx4 v[26:29], v[2:3], off offset:1024
	global_load_dwordx4 v[22:25], v[2:3], off offset:2048
	global_load_dwordx4 v[18:21], v[2:3], off offset:3072
	v_add_co_u32_e32 v2, vcc, 0x1000, v2
	s_nop 1
	v_addc_co_u32_e32 v3, vcc, 0, v3, vcc
	global_load_dwordx4 v[14:17], v[2:3], off
	global_load_dwordx4 v[10:13], v[2:3], off offset:1024
	global_load_dwordx4 v[6:9], v[2:3], off offset:2048
	s_nop 0
	global_load_dwordx4 v[2:5], v[2:3], off offset:3072
	s_cbranch_scc1 .LBB0_1562
	v_lshl_add_u64 v[36:37], v[34:35], 2, s[4:5]
	v_add_co_u32_e32 v192, vcc, 0x1000, v36
	s_nop 1
	v_addc_co_u32_e32 v193, vcc, 0, v37, vcc
	v_add_co_u32_e32 v194, vcc, 0x801000, v36
	s_nop 1
	v_addc_co_u32_e32 v195, vcc, 0, v37, vcc
	v_add_co_u32_e32 v196, vcc, 0x1001000, v36
	s_nop 1
	v_addc_co_u32_e32 v197, vcc, 0, v37, vcc
	v_add_co_u32_e32 v198, vcc, 0x1801000, v36
	s_nop 1
	v_addc_co_u32_e32 v199, vcc, 0, v37, vcc
	global_load_dwordx4 v[64:67], v[192:193], off offset:-4096
	global_load_dwordx4 v[68:71], v[194:195], off offset:-4096
	global_load_dwordx4 v[72:75], v[196:197], off offset:-4096
	global_load_dwordx4 v[76:79], v[198:199], off offset:-4096
	global_load_dwordx4 v[80:83], v[192:193], off offset:-3072
	global_load_dwordx4 v[84:87], v[194:195], off offset:-3072
	global_load_dwordx4 v[88:91], v[196:197], off offset:-3072
	global_load_dwordx4 v[92:95], v[198:199], off offset:-3072
	global_load_dwordx4 v[96:99], v[192:193], off offset:-2048
	global_load_dwordx4 v[100:103], v[194:195], off offset:-2048
	global_load_dwordx4 v[104:107], v[196:197], off offset:-2048
	global_load_dwordx4 v[108:111], v[198:199], off offset:-2048
	global_load_dwordx4 v[112:115], v[192:193], off offset:-1024
	global_load_dwordx4 v[116:119], v[194:195], off offset:-1024
	global_load_dwordx4 v[120:123], v[196:197], off offset:-1024
	global_load_dwordx4 v[124:127], v[198:199], off offset:-1024
	global_load_dwordx4 v[128:131], v[192:193], off
	global_load_dwordx4 v[132:135], v[194:195], off
	global_load_dwordx4 v[136:139], v[196:197], off
	global_load_dwordx4 v[140:143], v[198:199], off
	global_load_dwordx4 v[144:147], v[192:193], off offset:1024
	global_load_dwordx4 v[148:151], v[194:195], off offset:1024
	global_load_dwordx4 v[152:155], v[196:197], off offset:1024
	global_load_dwordx4 v[156:159], v[198:199], off offset:1024
	global_load_dwordx4 v[160:163], v[192:193], off offset:2048
	global_load_dwordx4 v[164:167], v[194:195], off offset:2048
	global_load_dwordx4 v[168:171], v[196:197], off offset:2048
	global_load_dwordx4 v[172:175], v[198:199], off offset:2048
	global_load_dwordx4 v[176:179], v[192:193], off offset:3072
	global_load_dwordx4 v[180:183], v[194:195], off offset:3072
	global_load_dwordx4 v[184:187], v[196:197], off offset:3072
	global_load_dwordx4 v[188:191], v[198:199], off offset:3072
	s_waitcnt vmcnt(0)
	v_pk_add_f32 v[50:51], v[66:67], v[70:71]
	v_pk_add_f32 v[52:53], v[64:65], v[68:69]
	v_pk_add_f32 v[42:43], v[74:75], v[78:79]
	v_pk_add_f32 v[40:41], v[72:73], v[76:77]
	v_pk_add_f32 v[42:43], v[50:51], v[42:43]
	v_pk_add_f32 v[40:41], v[52:53], v[40:41]
	v_pk_fma_f32 v[32:33], v[32:33], s[88:89], v[42:43] op_sel_hi:[1,0,1]
	v_pk_fma_f32 v[30:31], v[30:31], s[88:89], v[40:41] op_sel_hi:[1,0,1]
	v_pk_add_f32 v[50:51], v[82:83], v[86:87]
	v_pk_add_f32 v[52:53], v[80:81], v[84:85]
	v_pk_add_f32 v[42:43], v[90:91], v[94:95]
	v_pk_add_f32 v[40:41], v[88:89], v[92:93]
	v_pk_add_f32 v[42:43], v[50:51], v[42:43]
	v_pk_add_f32 v[40:41], v[52:53], v[40:41]
	v_pk_fma_f32 v[28:29], v[28:29], s[88:89], v[42:43] op_sel_hi:[1,0,1]
	v_pk_fma_f32 v[26:27], v[26:27], s[88:89], v[40:41] op_sel_hi:[1,0,1]
	v_pk_add_f32 v[50:51], v[98:99], v[102:103]
	v_pk_add_f32 v[52:53], v[96:97], v[100:101]
	v_pk_add_f32 v[42:43], v[106:107], v[110:111]
	v_pk_add_f32 v[40:41], v[104:105], v[108:109]
	v_pk_add_f32 v[42:43], v[50:51], v[42:43]
	v_pk_add_f32 v[40:41], v[52:53], v[40:41]
	v_pk_fma_f32 v[24:25], v[24:25], s[88:89], v[42:43] op_sel_hi:[1,0,1]
	v_pk_fma_f32 v[22:23], v[22:23], s[88:89], v[40:41] op_sel_hi:[1,0,1]
	v_pk_add_f32 v[50:51], v[114:115], v[118:119]
	v_pk_add_f32 v[52:53], v[112:113], v[116:117]
	v_pk_add_f32 v[42:43], v[122:123], v[126:127]
	v_pk_add_f32 v[40:41], v[120:121], v[124:125]
	v_pk_add_f32 v[42:43], v[50:51], v[42:43]
	v_pk_add_f32 v[40:41], v[52:53], v[40:41]
	v_pk_fma_f32 v[20:21], v[20:21], s[88:89], v[42:43] op_sel_hi:[1,0,1]
	v_pk_fma_f32 v[18:19], v[18:19], s[88:89], v[40:41] op_sel_hi:[1,0,1]
	v_pk_add_f32 v[50:51], v[130:131], v[134:135]
	v_pk_add_f32 v[52:53], v[128:129], v[132:133]
	v_pk_add_f32 v[42:43], v[138:139], v[142:143]
	v_pk_add_f32 v[40:41], v[136:137], v[140:141]
	v_pk_add_f32 v[42:43], v[50:51], v[42:43]
	v_pk_add_f32 v[40:41], v[52:53], v[40:41]
	v_pk_fma_f32 v[16:17], v[16:17], s[88:89], v[42:43] op_sel_hi:[1,0,1]
	v_pk_fma_f32 v[14:15], v[14:15], s[88:89], v[40:41] op_sel_hi:[1,0,1]
	v_pk_add_f32 v[50:51], v[146:147], v[150:151]
	v_pk_add_f32 v[52:53], v[144:145], v[148:149]
	v_pk_add_f32 v[42:43], v[154:155], v[158:159]
	v_pk_add_f32 v[40:41], v[152:153], v[156:157]
	v_pk_add_f32 v[42:43], v[50:51], v[42:43]
	v_pk_add_f32 v[40:41], v[52:53], v[40:41]
	v_pk_fma_f32 v[12:13], v[12:13], s[88:89], v[42:43] op_sel_hi:[1,0,1]
	v_pk_fma_f32 v[10:11], v[10:11], s[88:89], v[40:41] op_sel_hi:[1,0,1]
	v_pk_add_f32 v[50:51], v[162:163], v[166:167]
	v_pk_add_f32 v[52:53], v[160:161], v[164:165]
	v_pk_add_f32 v[42:43], v[170:171], v[174:175]
	v_pk_add_f32 v[40:41], v[168:169], v[172:173]
	v_pk_add_f32 v[42:43], v[50:51], v[42:43]
	v_pk_add_f32 v[40:41], v[52:53], v[40:41]
	v_pk_fma_f32 v[8:9], v[8:9], s[88:89], v[42:43] op_sel_hi:[1,0,1]
	v_pk_fma_f32 v[6:7], v[6:7], s[88:89], v[40:41] op_sel_hi:[1,0,1]
	v_pk_add_f32 v[50:51], v[178:179], v[182:183]
	v_pk_add_f32 v[52:53], v[176:177], v[180:181]
	v_pk_add_f32 v[42:43], v[186:187], v[190:191]
	v_pk_add_f32 v[40:41], v[184:185], v[188:189]
	v_pk_add_f32 v[42:43], v[50:51], v[42:43]
	v_pk_add_f32 v[40:41], v[52:53], v[40:41]
	v_pk_fma_f32 v[4:5], v[4:5], s[88:89], v[42:43] op_sel_hi:[1,0,1]
	v_pk_fma_f32 v[2:3], v[2:3], s[88:89], v[40:41] op_sel_hi:[1,0,1]

.LBB0_1916:
	s_cmp_eq_u64 s[22:23], 0
	v_lshlrev_b32_e32 v34, 2, v38
	v_ashrrev_i32_e32 v35, 31, v34
	s_waitcnt vmcnt(0)
	v_lshl_add_u64 v[2:3], v[34:35], 2, s[12:13]
	global_load_dwordx4 v[30:33], v[2:3], off
	global_load_dwordx4 v[26:29], v[2:3], off offset:1024
	global_load_dwordx4 v[22:25], v[2:3], off offset:2048
	global_load_dwordx4 v[18:21], v[2:3], off offset:3072
	v_add_co_u32_e32 v2, vcc, 0x1000, v2
	s_nop 1
	v_addc_co_u32_e32 v3, vcc, 0, v3, vcc
	global_load_dwordx4 v[14:17], v[2:3], off
	global_load_dwordx4 v[10:13], v[2:3], off offset:1024
	global_load_dwordx4 v[6:9], v[2:3], off offset:2048
	s_nop 0
	global_load_dwordx4 v[2:5], v[2:3], off offset:3072
	s_cbranch_scc1 .LBB0_1918
	v_lshl_add_u64 v[36:37], v[34:35], 2, s[22:23]
	v_add_co_u32_e32 v192, vcc, 0x1000, v36
	s_nop 1
	v_addc_co_u32_e32 v193, vcc, 0, v37, vcc
	v_add_co_u32_e32 v194, vcc, 0x801000, v36
	s_nop 1
	v_addc_co_u32_e32 v195, vcc, 0, v37, vcc
	v_add_co_u32_e32 v196, vcc, 0x1001000, v36
	s_nop 1
	v_addc_co_u32_e32 v197, vcc, 0, v37, vcc
	v_add_co_u32_e32 v198, vcc, 0x1801000, v36
	s_nop 1
	v_addc_co_u32_e32 v199, vcc, 0, v37, vcc
	global_load_dwordx4 v[64:67], v[192:193], off offset:-4096
	global_load_dwordx4 v[68:71], v[194:195], off offset:-4096
	global_load_dwordx4 v[72:75], v[196:197], off offset:-4096
	global_load_dwordx4 v[76:79], v[198:199], off offset:-4096
	global_load_dwordx4 v[80:83], v[192:193], off offset:-3072
	global_load_dwordx4 v[84:87], v[194:195], off offset:-3072
	global_load_dwordx4 v[88:91], v[196:197], off offset:-3072
	global_load_dwordx4 v[92:95], v[198:199], off offset:-3072
	global_load_dwordx4 v[96:99], v[192:193], off offset:-2048
	global_load_dwordx4 v[100:103], v[194:195], off offset:-2048
	global_load_dwordx4 v[104:107], v[196:197], off offset:-2048
	global_load_dwordx4 v[108:111], v[198:199], off offset:-2048
	global_load_dwordx4 v[112:115], v[192:193], off offset:-1024
	global_load_dwordx4 v[116:119], v[194:195], off offset:-1024
	global_load_dwordx4 v[120:123], v[196:197], off offset:-1024
	global_load_dwordx4 v[124:127], v[198:199], off offset:-1024
	global_load_dwordx4 v[128:131], v[192:193], off
	global_load_dwordx4 v[132:135], v[194:195], off
	global_load_dwordx4 v[136:139], v[196:197], off
	global_load_dwordx4 v[140:143], v[198:199], off
	global_load_dwordx4 v[144:147], v[192:193], off offset:1024
	global_load_dwordx4 v[148:151], v[194:195], off offset:1024
	global_load_dwordx4 v[152:155], v[196:197], off offset:1024
	global_load_dwordx4 v[156:159], v[198:199], off offset:1024
	global_load_dwordx4 v[160:163], v[192:193], off offset:2048
	global_load_dwordx4 v[164:167], v[194:195], off offset:2048
	global_load_dwordx4 v[168:171], v[196:197], off offset:2048
	global_load_dwordx4 v[172:175], v[198:199], off offset:2048
	global_load_dwordx4 v[176:179], v[192:193], off offset:3072
	global_load_dwordx4 v[180:183], v[194:195], off offset:3072
	global_load_dwordx4 v[184:187], v[196:197], off offset:3072
	global_load_dwordx4 v[188:191], v[198:199], off offset:3072
	s_waitcnt vmcnt(0)
	v_pk_add_f32 v[50:51], v[66:67], v[70:71]
	v_pk_add_f32 v[52:53], v[64:65], v[68:69]
	v_pk_add_f32 v[42:43], v[74:75], v[78:79]
	v_pk_add_f32 v[40:41], v[72:73], v[76:77]
	v_pk_add_f32 v[42:43], v[50:51], v[42:43]
	v_pk_add_f32 v[40:41], v[52:53], v[40:41]
	v_pk_fma_f32 v[32:33], v[32:33], s[88:89], v[42:43] op_sel_hi:[1,0,1]
	v_pk_fma_f32 v[30:31], v[30:31], s[88:89], v[40:41] op_sel_hi:[1,0,1]
	v_pk_add_f32 v[50:51], v[82:83], v[86:87]
	v_pk_add_f32 v[52:53], v[80:81], v[84:85]
	v_pk_add_f32 v[42:43], v[90:91], v[94:95]
	v_pk_add_f32 v[40:41], v[88:89], v[92:93]
	v_pk_add_f32 v[42:43], v[50:51], v[42:43]
	v_pk_add_f32 v[40:41], v[52:53], v[40:41]
	v_pk_fma_f32 v[28:29], v[28:29], s[88:89], v[42:43] op_sel_hi:[1,0,1]
	v_pk_fma_f32 v[26:27], v[26:27], s[88:89], v[40:41] op_sel_hi:[1,0,1]
	v_pk_add_f32 v[50:51], v[98:99], v[102:103]
	v_pk_add_f32 v[52:53], v[96:97], v[100:101]
	v_pk_add_f32 v[42:43], v[106:107], v[110:111]
	v_pk_add_f32 v[40:41], v[104:105], v[108:109]
	v_pk_add_f32 v[42:43], v[50:51], v[42:43]
	v_pk_add_f32 v[40:41], v[52:53], v[40:41]
	v_pk_fma_f32 v[24:25], v[24:25], s[88:89], v[42:43] op_sel_hi:[1,0,1]
	v_pk_fma_f32 v[22:23], v[22:23], s[88:89], v[40:41] op_sel_hi:[1,0,1]
	v_pk_add_f32 v[50:51], v[114:115], v[118:119]
	v_pk_add_f32 v[52:53], v[112:113], v[116:117]
	v_pk_add_f32 v[42:43], v[122:123], v[126:127]
	v_pk_add_f32 v[40:41], v[120:121], v[124:125]
	v_pk_add_f32 v[42:43], v[50:51], v[42:43]
	v_pk_add_f32 v[40:41], v[52:53], v[40:41]
	v_pk_fma_f32 v[20:21], v[20:21], s[88:89], v[42:43] op_sel_hi:[1,0,1]
	v_pk_fma_f32 v[18:19], v[18:19], s[88:89], v[40:41] op_sel_hi:[1,0,1]
	v_pk_add_f32 v[50:51], v[130:131], v[134:135]
	v_pk_add_f32 v[52:53], v[128:129], v[132:133]
	v_pk_add_f32 v[42:43], v[138:139], v[142:143]
	v_pk_add_f32 v[40:41], v[136:137], v[140:141]
	v_pk_add_f32 v[42:43], v[50:51], v[42:43]
	v_pk_add_f32 v[40:41], v[52:53], v[40:41]
	v_pk_fma_f32 v[16:17], v[16:17], s[88:89], v[42:43] op_sel_hi:[1,0,1]
	v_pk_fma_f32 v[14:15], v[14:15], s[88:89], v[40:41] op_sel_hi:[1,0,1]
	v_pk_add_f32 v[50:51], v[146:147], v[150:151]
	v_pk_add_f32 v[52:53], v[144:145], v[148:149]
	v_pk_add_f32 v[42:43], v[154:155], v[158:159]
	v_pk_add_f32 v[40:41], v[152:153], v[156:157]
	v_pk_add_f32 v[42:43], v[50:51], v[42:43]
	v_pk_add_f32 v[40:41], v[52:53], v[40:41]
	v_pk_fma_f32 v[12:13], v[12:13], s[88:89], v[42:43] op_sel_hi:[1,0,1]
	v_pk_fma_f32 v[10:11], v[10:11], s[88:89], v[40:41] op_sel_hi:[1,0,1]
	v_pk_add_f32 v[50:51], v[162:163], v[166:167]
	v_pk_add_f32 v[52:53], v[160:161], v[164:165]
	v_pk_add_f32 v[42:43], v[170:171], v[174:175]
	v_pk_add_f32 v[40:41], v[168:169], v[172:173]
	v_pk_add_f32 v[42:43], v[50:51], v[42:43]
	v_pk_add_f32 v[40:41], v[52:53], v[40:41]
	v_pk_fma_f32 v[8:9], v[8:9], s[88:89], v[42:43] op_sel_hi:[1,0,1]
	v_pk_fma_f32 v[6:7], v[6:7], s[88:89], v[40:41] op_sel_hi:[1,0,1]
	v_pk_add_f32 v[50:51], v[178:179], v[182:183]
	v_pk_add_f32 v[52:53], v[176:177], v[180:181]
	v_pk_add_f32 v[42:43], v[186:187], v[190:191]
	v_pk_add_f32 v[40:41], v[184:185], v[188:189]
	v_pk_add_f32 v[42:43], v[50:51], v[42:43]
	v_pk_add_f32 v[40:41], v[52:53], v[40:41]
	v_pk_fma_f32 v[4:5], v[4:5], s[88:89], v[42:43] op_sel_hi:[1,0,1]
	v_pk_fma_f32 v[2:3], v[2:3], s[88:89], v[40:41] op_sel_hi:[1,0,1]
